# scan tail: four output stores use distinct address registers, issued back to back
# baseline (speedup 1.0000x reference)
; #define LAS __attribute__((address_space(3)))
; __device__ __forceinline__ void scan2_phase(KA a, LAS unsigned char* lds, int G, const int tid, const int bid) {
;     ...
;             const u32x2 z2 = (u32x2){0u, 0u};
;             bf16x8 sb[2];
; #pragma unroll
;             for (int kb = 0; kb < 2; ++kb) { u32x4 w; w.x = pk2(accS[2 * kb][0], accS[2 * kb][1]); w.y = pk2(accS[2 * kb][2], accS[2 * kb][3]); w.z = pk2(accS[2 * kb + 1][0], accS[2 * kb + 1][1]); w.w = pk2(accS[2 * kb + 1][2], accS[2 * kb + 1][3]); sb[kb] = __builtin_bit_cast(bf16x8, w); }
;             const u32x2 vlo = *(const LAS u32x2*)(VT + (16 * r + fr) * 24 + 4 * fq);
;             f32x4 accX = (f32x4){0.f, 0.f, 0.f, 0.f}, accY = (f32x4){0.f, 0.f, 0.f, 0.f};
; #pragma unroll
;             for (int kb = 0; kb < 2; ++kb) { const u32x2 lo = *(const LAS u32x2*)(At + fr * 72 + 32 * kb + 4 * fq), hi = *(const LAS u32x2*)(At + fr * 72 + 32 * kb + 16 + 4 * fq); accX = __builtin_amdgcn_mfma_f32_16x16x32_bf16(mk8(lo, hi), sb[kb], accX, 0, 0, 0); }
;             { const u32x2 alo = *(const LAS u32x2*)(MkaT + fr * 24 + 4 * fq); accX = __builtin_amdgcn_mfma_f32_16x16x32_bf16(mk8(alo, z2), mk8(vlo, z2), accX, 0, 0, 0); }
; #pragma unroll
;             for (int kb = 0; kb < 2; ++kb) { const u32x2 lo = *(const LAS u32x2*)(Rt + fr * 72 + 32 * kb + 4 * fq), hi = *(const LAS u32x2*)(Rt + fr * 72 + 32 * kb + 16 + 4 * fq); accY = __builtin_amdgcn_mfma_f32_16x16x32_bf16(mk8(lo, hi), sb[kb], accY, 0, 0, 0); }
;             {
;                 f32x4 accSA = (f32x4){0.f, 0.f, 0.f, 0.f};
; #pragma unroll
;                 for (int kk = 0; kk < 4; ++kk) accSA = __builtin_amdgcn_mfma_f32_16x16x4f32(TTf[fr * 20 + 4 * fq + kk], accX[kk], accSA, 0, 0, 0);
;                 u32x2 sav; sav.x = pk2(accSA[0], accSA[1]); sav.y = pk2(accSA[2], accSA[3]);
;                 const bf16x8 bsv = mk8(sav, vlo);
;                 { const u32x2 lo = *(const LAS u32x2*)(MbrT + fr * 24 + 4 * fq), hi = *(const LAS u32x2*)(MkrT + fr * 24 + 4 * fq); accY = __builtin_amdgcn_mfma_f32_16x16x32_bf16(mk8(lo, hi), bsv, accY, 0, 0, 0); }
; #pragma unroll
;                 for (int i = 0; i < 4; ++i) { const int tau = b * 16 + 4 * fq + i; const int t = dir ? len - 1 - tau : tau; Y[(size_t)(row0 + t) * 512 + h * 64 + 16 * r + fr] = (bf16_t)f2bf(accY[i]); }
; #pragma unroll
;                 for (int jt = 0; jt < 4; ++jt) {
.LBB0_180:
	v_lshl_add_u32 v52, v78, 1, s84
	s_waitcnt lgkmcnt(0)
	s_barrier
	v_add_u32_e32 v44, v52, v135
	v_add_u32_e32 v16, v52, v91
	ds_read2_b64 v[32:35], v44 offset1:4
	ds_read2_b64 v[36:39], v44 offset0:8 offset1:12
	v_add_u32_e32 v53, v44, v115
	ds_read_b64 v[242:243], v16 offset:15360
	ds_read_b64 v[246:247], v53 offset:18432
	v_add_u32_e32 v40, 0x800, v44
	ds_read2_b64 v[60:63], v40 offset0:32 offset1:36
	ds_read2_b64 v[64:67], v40 offset0:40 offset1:44
	v_lshlrev_b32_e32 v18, 2, v78
	v_add3_u32 v18, s84, v93, v18
	ds_read_b128 v[56:59], v18 offset:22016
	ds_read_b64 v[202:203], v53 offset:19200
	ds_read_b64 v[204:205], v53 offset:19968
	ds_read_b64 v[208:209], v16 offset:15360
	v_cvt_pk_bf16_f32 v20, v12, v13
	v_cvt_pk_bf16_f32 v21, v14, v15
	v_cvt_pk_bf16_f32 v22, v0, v1
	v_cvt_pk_bf16_f32 v23, v2, v3
	v_cvt_pk_bf16_f32 v24, v4, v5
	v_cvt_pk_bf16_f32 v25, v6, v7
	v_cvt_pk_bf16_f32 v26, v8, v9
	v_cvt_pk_bf16_f32 v27, v10, v11
	v_lshl_add_u32 v17, v92, 1, v52
	s_waitcnt lgkmcnt(9)
	v_mfma_f32_16x16x32_bf16 v[32:35], v[32:35], v[20:23], 0
	s_waitcnt lgkmcnt(8)
	v_mfma_f32_16x16x32_bf16 v[32:35], v[36:39], v[24:27], v[32:35]
	s_waitcnt lgkmcnt(5)
	v_mfma_f32_16x16x32_bf16 v[68:71], v[60:63], v[20:23], 0
	v_mfma_f32_16x16x32_bf16 v[32:35], v[246:249], v[242:245], v[32:35]
	s_waitcnt lgkmcnt(4)
	v_mfma_f32_16x16x32_bf16 v[68:71], v[64:67], v[24:27], v[68:71]
	s_waitcnt lgkmcnt(0)
	ds_read_b64 v[210:211], v17 offset:9216
	ds_read_b64 v[212:213], v17 offset:12288
	ds_read_b64 v[214:215], v17 offset:9984
	ds_read_b64 v[216:217], v17 offset:13056
	ds_read_b64 v[218:219], v17 offset:10752
	ds_read_b64 v[220:221], v17 offset:13824
	ds_read_b64 v[222:223], v17 offset:11520
	ds_read_b64 v[224:225], v17 offset:14592
	v_add_u32_e32 v16, v52, v79
	ds_read_b128 v[182:185], v16 offset:23296
	ds_read_b128 v[186:189], v16 offset:23360
	ds_read_b128 v[190:193], v16 offset:23424
	ds_read_b128 v[194:197], v16 offset:23488
	v_mfma_f32_16x16x4_f32 v[72:75], v56, v32, 0
	v_mfma_f32_16x16x4_f32 v[72:75], v57, v33, v[72:75]
	v_mfma_f32_16x16x4_f32 v[72:75], v58, v34, v[72:75]
	v_mfma_f32_16x16x4_f32 v[72:75], v59, v35, v[72:75]
	s_nop 10
	v_cvt_pk_bf16_f32 v206, v72, v73
	v_cvt_pk_bf16_f32 v207, v74, v75
	s_nop 1
	v_mfma_f32_16x16x32_bf16 v[68:71], v[202:205], v[206:209], v[68:71]
	s_waitcnt lgkmcnt(10)
	v_mfma_f32_16x16x32_bf16 v[12:15], v[210:213], v[206:209], v[12:15]
	s_waitcnt lgkmcnt(8)
	v_mfma_f32_16x16x32_bf16 v[0:3], v[214:217], v[206:209], v[0:3]
	s_waitcnt lgkmcnt(6)
	v_mfma_f32_16x16x32_bf16 v[4:7], v[218:221], v[206:209], v[4:7]
	s_waitcnt lgkmcnt(4)
	v_mfma_f32_16x16x32_bf16 v[8:11], v[222:225], v[206:209], v[8:11]
	s_nop 1
	v_lshl_add_u64 v[56:57], v[250:251], 0, v[252:253]
	v_lshl_add_u64 v[58:59], v[56:57], 0, v[252:253]
	v_lshl_add_u64 v[60:61], v[58:59], 0, v[252:253]
	v_cvt_pk_bf16_f32 v24, v68, s0
	v_cvt_pk_bf16_f32 v25, v69, s0
	v_cvt_pk_bf16_f32 v26, v70, s0
	v_cvt_pk_bf16_f32 v27, v71, s0
	global_store_short v[250:251], v24, off
	global_store_short v[56:57], v25, off
	global_store_short v[58:59], v26, off
	global_store_short v[60:61], v27, off
	s_waitcnt lgkmcnt(0)
	v_pk_mul_f32 v[12:13], v[12:13], v[182:183]
	v_pk_mul_f32 v[14:15], v[14:15], v[184:185]
	v_pk_mul_f32 v[0:1], v[0:1], v[186:187]
	v_pk_mul_f32 v[2:3], v[2:3], v[188:189]
	v_pk_mul_f32 v[4:5], v[4:5], v[190:191]
	v_pk_mul_f32 v[6:7], v[6:7], v[192:193]
	v_pk_mul_f32 v[8:9], v[8:9], v[194:195]
	v_pk_mul_f32 v[10:11], v[10:11], v[196:197]
	v_lshl_add_u64 v[250:251], v[252:253], 4, v[250:251]
	s_add_i32 s81, s81, 16
	s_add_i32 s30, s30, -16
	s_cmp_eq_u32 s82, s83
	s_cbranch_scc1 .LBB0_173
